# stack2 + early buffer_wbl2 by the last 3 non-leader workgroups arriving at each grid barrier (L2 writeback started before the XCD leader's release fence)
# speedup vs baseline: 1.0045x; 1.0045x over previous
; __device__ __forceinline__ unsigned xb_ld(unsigned* p)              { return __hip_atomic_load(p, __ATOMIC_RELAXED, __HIP_MEMORY_SCOPE_AGENT); }
; __device__ __forceinline__ unsigned xb_add(unsigned* p, unsigned v) { return __hip_atomic_fetch_add(p, v, __ATOMIC_RELAXED, __HIP_MEMORY_SCOPE_AGENT); }
; #define XB_SPIN(cond, bar) do { unsigned _sp = 0; while (cond) { __builtin_amdgcn_s_sleep(1); \
;     if ((++_sp & 255u) == 0u) { if (xb_ld(&(bar)[XB_TMO])) break; if (_sp > XB_SPIN_CAP) { atomicAdd(&(bar)[XB_TMO], 1u); break; } } } } while (0)
; __device__ __forceinline__ void xcd_barrier(const XcdBarrier& b) {
;     ...
;         const unsigned old = xb_add(&bar[XB_XSUB(b.x)], 1u);
;         const unsigned gen = old / nloc;
;         if (old + 1u == (gen + 1u) * nloc) {
;             __builtin_amdgcn_fence(__ATOMIC_RELEASE, "agent");
;             asm volatile("s_waitcnt vmcnt(0)" ::: "memory");
;             const unsigned og = xb_add(&bar[XB_TOP], 1u);
;             const unsigned tg = og / nx;
;             if (og + 1u == (tg + 1u) * nx) xb_add(&bar[XB_TOPGEN], 1u);
;             else XB_SPIN(xb_ld(&bar[XB_TOPGEN]) == tg, bar);
;             __builtin_amdgcn_fence(__ATOMIC_ACQUIRE, "agent");
;             xb_add(&bar[XB_XGEN(b.x)], 1u);
;             asm volatile("s_waitcnt vmcnt(0)" ::: "memory");
;         } else {
;             XB_SPIN(xb_ld(&bar[XB_XGEN(b.x)]) == gen, bar);
.LBB0_100:
	s_or_b64 exec, exec, s[10:11]
	v_cvt_f32_u32_e32 v5, v3
	s_waitcnt vmcnt(0)
	v_readfirstlane_b32 s8, v4
	v_sub_u32_e32 v4, 0, v3
	v_rcp_iflag_f32_e32 v5, v5
	v_add_u32_e32 v6, s8, v2
	v_mul_f32_e32 v5, 0x4f7ffffe, v5
	v_cvt_u32_f32_e32 v5, v5
	v_mul_lo_u32 v2, v4, v5
	v_mul_hi_u32 v2, v5, v2
	v_add_u32_e32 v2, v5, v2
	v_mul_hi_u32 v2, v6, v2
	v_mul_lo_u32 v4, v2, v3
	v_sub_u32_e32 v4, v6, v4
	v_add_u32_e32 v5, 1, v2
	v_cmp_ge_u32_e32 vcc, v4, v3
	s_nop 1
	v_cndmask_b32_e32 v2, v2, v5, vcc
	v_sub_u32_e32 v5, v4, v3
	v_cndmask_b32_e32 v4, v4, v5, vcc
	v_add_u32_e32 v5, 1, v2
	v_cmp_ge_u32_e32 vcc, v4, v3
	v_add_u32_e32 v4, 1, v6
	s_nop 0
	v_cndmask_b32_e32 v2, v2, v5, vcc
	v_mul_lo_u32 v5, v3, v2
	v_add_u32_e32 v3, v5, v3
	v_cmp_ne_u32_e32 vcc, v4, v3
	s_and_saveexec_b64 s[8:9], vcc
	s_xor_b64 s[8:9], exec, s[8:9]
	s_cbranch_execz .LBB0_114
	v_sub_u32_e32 v1, v3, v4
	s_nop 0
	v_readfirstlane_b32 s14, v1
	s_cmp_le_u32 s14, 3
	s_cbranch_scc0 .Lskip_wb0
	buffer_wbl2 sc1
.Lskip_wb0:
	s_waitcnt lgkmcnt(0)
	v_mov_b32_e32 v1, 0x2000
	global_load_dword v1, v1, s[6:7] offset:1024 sc1
	s_add_u32 s14, s6, 0x2400
	s_addc_u32 s15, s7, 0
	s_waitcnt vmcnt(0)
	v_cmp_eq_u32_e32 vcc, v1, v2
	s_and_saveexec_b64 s[10:11], vcc
	s_cbranch_execz .LBB0_113
	s_add_u32 s12, s64, 0x4200
	s_addc_u32 s13, s65, 0
	s_mov_b32 s26, 1
	s_mov_b64 s[16:17], 0
	v_mov_b32_e32 v1, 0
	s_branch .LBB0_104

; __device__ __forceinline__ unsigned xb_ld(unsigned* p)              { return __hip_atomic_load(p, __ATOMIC_RELAXED, __HIP_MEMORY_SCOPE_AGENT); }
; __device__ __forceinline__ unsigned xb_add(unsigned* p, unsigned v) { return __hip_atomic_fetch_add(p, v, __ATOMIC_RELAXED, __HIP_MEMORY_SCOPE_AGENT); }
; #define XB_SPIN(cond, bar) do { unsigned _sp = 0; while (cond) { __builtin_amdgcn_s_sleep(1); \
;     if ((++_sp & 255u) == 0u) { if (xb_ld(&(bar)[XB_TMO])) break; if (_sp > XB_SPIN_CAP) { atomicAdd(&(bar)[XB_TMO], 1u); break; } } } } while (0)
; __device__ __forceinline__ void xcd_barrier(const XcdBarrier& b) {
;     ...
;         const unsigned old = xb_add(&bar[XB_XSUB(b.x)], 1u);
;         const unsigned gen = old / nloc;
;         if (old + 1u == (gen + 1u) * nloc) {
;             __builtin_amdgcn_fence(__ATOMIC_RELEASE, "agent");
;             asm volatile("s_waitcnt vmcnt(0)" ::: "memory");
;             const unsigned og = xb_add(&bar[XB_TOP], 1u);
;             const unsigned tg = og / nx;
;             if (og + 1u == (tg + 1u) * nx) xb_add(&bar[XB_TOPGEN], 1u);
;             else XB_SPIN(xb_ld(&bar[XB_TOPGEN]) == tg, bar);
;             __builtin_amdgcn_fence(__ATOMIC_ACQUIRE, "agent");
;             xb_add(&bar[XB_XGEN(b.x)], 1u);
;             asm volatile("s_waitcnt vmcnt(0)" ::: "memory");
;         } else {
;             XB_SPIN(xb_ld(&bar[XB_XGEN(b.x)]) == gen, bar);
.LBB0_238:
	s_or_b64 exec, exec, s[12:13]
	v_cvt_f32_u32_e32 v6, v4
	s_waitcnt vmcnt(0)
	v_readfirstlane_b32 s3, v5
	v_sub_u32_e32 v5, 0, v4
	v_rcp_iflag_f32_e32 v6, v6
	v_add_u32_e32 v7, s3, v3
	v_mul_f32_e32 v6, 0x4f7ffffe, v6
	v_cvt_u32_f32_e32 v6, v6
	v_mul_lo_u32 v3, v5, v6
	v_mul_hi_u32 v3, v6, v3
	v_add_u32_e32 v3, v6, v3
	v_mul_hi_u32 v3, v7, v3
	v_mul_lo_u32 v5, v3, v4
	v_sub_u32_e32 v5, v7, v5
	v_add_u32_e32 v6, 1, v3
	v_cmp_ge_u32_e32 vcc, v5, v4
	s_nop 1
	v_cndmask_b32_e32 v3, v3, v6, vcc
	v_sub_u32_e32 v6, v5, v4
	v_cndmask_b32_e32 v5, v5, v6, vcc
	v_add_u32_e32 v6, 1, v3
	v_cmp_ge_u32_e32 vcc, v5, v4
	v_add_u32_e32 v5, 1, v7
	s_nop 0
	v_cndmask_b32_e32 v3, v3, v6, vcc
	v_mul_lo_u32 v6, v4, v3
	v_add_u32_e32 v4, v6, v4
	v_cmp_ne_u32_e32 vcc, v5, v4
	s_and_saveexec_b64 s[12:13], vcc
	s_xor_b64 s[18:19], exec, s[12:13]
	s_cbranch_execz .LBB0_252
	v_sub_u32_e32 v2, v4, v5
	s_nop 0
	v_readfirstlane_b32 s3, v2
	s_cmp_le_u32 s3, 3
	s_cbranch_scc0 .Lskip_wb1
	buffer_wbl2 sc1
.Lskip_wb1:
	v_readlane_b32 s12, v254, 17
	v_readlane_b32 s13, v254, 18
	s_waitcnt lgkmcnt(0)
	s_nop 3
	global_load_dword v2, v179, s[12:13] sc1
	s_waitcnt vmcnt(0)
	v_cmp_eq_u32_e32 vcc, v2, v3
	s_and_saveexec_b64 s[38:39], vcc
	s_cbranch_execz .LBB0_251
	s_mov_b32 s3, 1
	s_mov_b64 s[40:41], 0
	s_branch .LBB0_242

; __device__ __forceinline__ unsigned xb_ld(unsigned* p)              { return __hip_atomic_load(p, __ATOMIC_RELAXED, __HIP_MEMORY_SCOPE_AGENT); }
; __device__ __forceinline__ unsigned xb_add(unsigned* p, unsigned v) { return __hip_atomic_fetch_add(p, v, __ATOMIC_RELAXED, __HIP_MEMORY_SCOPE_AGENT); }
; #define XB_SPIN(cond, bar) do { unsigned _sp = 0; while (cond) { __builtin_amdgcn_s_sleep(1); \
;     if ((++_sp & 255u) == 0u) { if (xb_ld(&(bar)[XB_TMO])) break; if (_sp > XB_SPIN_CAP) { atomicAdd(&(bar)[XB_TMO], 1u); break; } } } } while (0)
; __device__ __forceinline__ void xcd_barrier(const XcdBarrier& b) {
;     ...
;         const unsigned old = xb_add(&bar[XB_XSUB(b.x)], 1u);
;         const unsigned gen = old / nloc;
;         if (old + 1u == (gen + 1u) * nloc) {
;             __builtin_amdgcn_fence(__ATOMIC_RELEASE, "agent");
;             asm volatile("s_waitcnt vmcnt(0)" ::: "memory");
;             const unsigned og = xb_add(&bar[XB_TOP], 1u);
;             const unsigned tg = og / nx;
;             if (og + 1u == (tg + 1u) * nx) xb_add(&bar[XB_TOPGEN], 1u);
;             else XB_SPIN(xb_ld(&bar[XB_TOPGEN]) == tg, bar);
;             __builtin_amdgcn_fence(__ATOMIC_ACQUIRE, "agent");
;             xb_add(&bar[XB_XGEN(b.x)], 1u);
;             asm volatile("s_waitcnt vmcnt(0)" ::: "memory");
;         } else {
;             XB_SPIN(xb_ld(&bar[XB_XGEN(b.x)]) == gen, bar);
.LBB0_1022:
	s_or_b64 exec, exec, s[12:13]
	v_cvt_f32_u32_e32 v6, v4
	s_waitcnt vmcnt(0)
	v_readfirstlane_b32 s2, v5
	v_sub_u32_e32 v5, 0, v4
	v_rcp_iflag_f32_e32 v6, v6
	v_add_u32_e32 v7, s2, v3
	v_mul_f32_e32 v6, 0x4f7ffffe, v6
	v_cvt_u32_f32_e32 v6, v6
	v_mul_lo_u32 v3, v5, v6
	v_mul_hi_u32 v3, v6, v3
	v_add_u32_e32 v3, v6, v3
	v_mul_hi_u32 v3, v7, v3
	v_mul_lo_u32 v5, v3, v4
	v_sub_u32_e32 v5, v7, v5
	v_add_u32_e32 v6, 1, v3
	v_cmp_ge_u32_e32 vcc, v5, v4
	s_nop 1
	v_cndmask_b32_e32 v3, v3, v6, vcc
	v_sub_u32_e32 v6, v5, v4
	v_cndmask_b32_e32 v5, v5, v6, vcc
	v_add_u32_e32 v6, 1, v3
	v_cmp_ge_u32_e32 vcc, v5, v4
	v_add_u32_e32 v5, 1, v7
	s_nop 0
	v_cndmask_b32_e32 v3, v3, v6, vcc
	v_mul_lo_u32 v6, v4, v3
	v_add_u32_e32 v4, v6, v4
	v_cmp_ne_u32_e32 vcc, v5, v4
	s_and_saveexec_b64 s[2:3], vcc
	s_xor_b64 s[18:19], exec, s[2:3]
	s_cbranch_execz .LBB0_1036
	v_sub_u32_e32 v2, v4, v5
	s_nop 0
	v_readfirstlane_b32 s3, v2
	s_cmp_le_u32 s3, 3
	s_cbranch_scc0 .Lskip_wb8
	buffer_wbl2 sc1
.Lskip_wb8:
	v_readlane_b32 s2, v254, 17
	v_readlane_b32 s3, v254, 18
	s_waitcnt lgkmcnt(0)
	s_nop 3
	global_load_dword v2, v179, s[2:3] sc1
	s_waitcnt vmcnt(0)
	v_cmp_eq_u32_e32 vcc, v2, v3
	s_and_saveexec_b64 s[38:39], vcc
	s_cbranch_execz .LBB0_1035
	s_mov_b32 s2, 1
	s_mov_b64 s[40:41], 0
	s_branch .LBB0_1026
